# attention output rows stored write-through (sc1): less dirty L2 to write back at the release of the following grid barrier
# speedup vs baseline: 1.0156x; 1.0059x over previous
; __device__ __forceinline__ unsigned cvt_pk_bf16(float lo, float hi) { f32x2 f = {lo, hi}; bf16x2_t v = __builtin_convertvector(f, bf16x2_t); return __builtin_bit_cast(unsigned, v); }
; __device__ __forceinline__ void ph_attn(const Params& p, LAS unsigned char* lds) {
;     ...
;         if (active) {
;             bf16_t* dst = ao + (size_t)(r0 + w * 16 + fr) * D + h * 256 + fq * 4;
; #pragma unroll
;             for (int dt = 0; dt < 16; ++dt) { u32x2 wv; wv.x = cvt_pk_bf16(oa[dt][0] * linv, oa[dt][1] * linv); wv.y = cvt_pk_bf16(oa[dt][2] * linv, oa[dt][3] * linv); *(u32x2*)(dst + dt * 16) = wv; }
;         }
.LBB0_1108:
	s_and_b64 vcc, exec, s[12:13]
	s_cbranch_vccz .LBB0_1083
	v_pk_mul_f32 v[36:37], v[192:193], v[176:177] op_sel_hi:[0,1]
	v_pk_mul_f32 v[38:39], v[192:193], v[178:179] op_sel_hi:[0,1]
	v_cvt_pk_bf16_f32 v36, v36, v37
	v_cvt_pk_bf16_f32 v37, v38, v39
	ds_write_b64 v206, v[36:37]
	v_pk_mul_f32 v[40:41], v[192:193], v[172:173] op_sel_hi:[0,1]
	v_pk_mul_f32 v[42:43], v[192:193], v[174:175] op_sel_hi:[0,1]
	v_cvt_pk_bf16_f32 v40, v40, v41
	v_cvt_pk_bf16_f32 v41, v42, v43
	ds_write_b64 v206, v[40:41] offset:32
	v_pk_mul_f32 v[36:37], v[192:193], v[168:169] op_sel_hi:[0,1]
	v_pk_mul_f32 v[38:39], v[192:193], v[170:171] op_sel_hi:[0,1]
	v_cvt_pk_bf16_f32 v36, v36, v37
	v_cvt_pk_bf16_f32 v37, v38, v39
	ds_write_b64 v206, v[36:37] offset:64
	v_pk_mul_f32 v[40:41], v[192:193], v[164:165] op_sel_hi:[0,1]
	v_pk_mul_f32 v[42:43], v[192:193], v[166:167] op_sel_hi:[0,1]
	v_cvt_pk_bf16_f32 v40, v40, v41
	v_cvt_pk_bf16_f32 v41, v42, v43
	ds_write_b64 v206, v[40:41] offset:96
	v_pk_mul_f32 v[36:37], v[192:193], v[160:161] op_sel_hi:[0,1]
	v_pk_mul_f32 v[38:39], v[192:193], v[162:163] op_sel_hi:[0,1]
	v_cvt_pk_bf16_f32 v36, v36, v37
	v_cvt_pk_bf16_f32 v37, v38, v39
	ds_write_b64 v206, v[36:37] offset:128
	v_pk_mul_f32 v[40:41], v[192:193], v[156:157] op_sel_hi:[0,1]
	v_pk_mul_f32 v[42:43], v[192:193], v[158:159] op_sel_hi:[0,1]
	v_cvt_pk_bf16_f32 v40, v40, v41
	v_cvt_pk_bf16_f32 v41, v42, v43
	ds_write_b64 v206, v[40:41] offset:160
	v_pk_mul_f32 v[36:37], v[192:193], v[152:153] op_sel_hi:[0,1]
	v_pk_mul_f32 v[38:39], v[192:193], v[154:155] op_sel_hi:[0,1]
	v_cvt_pk_bf16_f32 v36, v36, v37
	v_cvt_pk_bf16_f32 v37, v38, v39
	ds_write_b64 v206, v[36:37] offset:192
	v_pk_mul_f32 v[40:41], v[192:193], v[148:149] op_sel_hi:[0,1]
	v_pk_mul_f32 v[42:43], v[192:193], v[150:151] op_sel_hi:[0,1]
	v_cvt_pk_bf16_f32 v40, v40, v41
	v_cvt_pk_bf16_f32 v41, v42, v43
	ds_write_b64 v206, v[40:41] offset:224
	v_pk_mul_f32 v[36:37], v[192:193], v[144:145] op_sel_hi:[0,1]
	v_pk_mul_f32 v[38:39], v[192:193], v[146:147] op_sel_hi:[0,1]
	v_cvt_pk_bf16_f32 v36, v36, v37
	v_cvt_pk_bf16_f32 v37, v38, v39
	ds_write_b64 v206, v[36:37] offset:256
	v_pk_mul_f32 v[40:41], v[192:193], v[140:141] op_sel_hi:[0,1]
	v_pk_mul_f32 v[42:43], v[192:193], v[142:143] op_sel_hi:[0,1]
	v_cvt_pk_bf16_f32 v40, v40, v41
	v_cvt_pk_bf16_f32 v41, v42, v43
	ds_write_b64 v206, v[40:41] offset:288
	v_pk_mul_f32 v[36:37], v[192:193], v[136:137] op_sel_hi:[0,1]
	v_pk_mul_f32 v[38:39], v[192:193], v[138:139] op_sel_hi:[0,1]
	v_cvt_pk_bf16_f32 v36, v36, v37
	v_cvt_pk_bf16_f32 v37, v38, v39
	ds_write_b64 v206, v[36:37] offset:320
	v_pk_mul_f32 v[40:41], v[192:193], v[132:133] op_sel_hi:[0,1]
	v_pk_mul_f32 v[42:43], v[192:193], v[134:135] op_sel_hi:[0,1]
	v_cvt_pk_bf16_f32 v40, v40, v41
	v_cvt_pk_bf16_f32 v41, v42, v43
	ds_write_b64 v206, v[40:41] offset:352
	v_pk_mul_f32 v[36:37], v[192:193], v[128:129] op_sel_hi:[0,1]
	v_pk_mul_f32 v[38:39], v[192:193], v[130:131] op_sel_hi:[0,1]
	v_cvt_pk_bf16_f32 v36, v36, v37
	v_cvt_pk_bf16_f32 v37, v38, v39
	ds_write_b64 v206, v[36:37] offset:384
	v_pk_mul_f32 v[40:41], v[192:193], v[124:125] op_sel_hi:[0,1]
	v_pk_mul_f32 v[42:43], v[192:193], v[126:127] op_sel_hi:[0,1]
	v_cvt_pk_bf16_f32 v40, v40, v41
	v_cvt_pk_bf16_f32 v41, v42, v43
	ds_write_b64 v206, v[40:41] offset:416
	v_pk_mul_f32 v[36:37], v[192:193], v[120:121] op_sel_hi:[0,1]
	v_pk_mul_f32 v[38:39], v[192:193], v[122:123] op_sel_hi:[0,1]
	v_cvt_pk_bf16_f32 v36, v36, v37
	v_cvt_pk_bf16_f32 v37, v38, v39
	ds_write_b64 v206, v[36:37] offset:448
	v_pk_mul_f32 v[40:41], v[192:193], v[116:117] op_sel_hi:[0,1]
	v_pk_mul_f32 v[42:43], v[192:193], v[118:119] op_sel_hi:[0,1]
	v_cvt_pk_bf16_f32 v40, v40, v41
	v_cvt_pk_bf16_f32 v41, v42, v43
	ds_write_b64 v206, v[40:41] offset:480
	s_waitcnt lgkmcnt(0)
	ds_read_b128 v[44:47], v205
	ds_read_b128 v[48:51], v205 offset:1056
	ds_read_b128 v[52:55], v205 offset:2112
	ds_read_b128 v[56:59], v205 offset:3168
	ds_read_b128 v[60:63], v205 offset:4224
	ds_read_b128 v[64:67], v205 offset:5280
	ds_read_b128 v[68:71], v205 offset:6336
	ds_read_b128 v[72:75], v205 offset:7392
	v_add_u32_e32 v217, 0x1000, v204
	v_add_u32_e32 v218, 0x2000, v204
	v_add_u32_e32 v219, 0x3000, v204
	v_add_u32_e32 v220, 0x4000, v204
	v_add_u32_e32 v221, 0x5000, v204
	v_add_u32_e32 v222, 0x6000, v204
	v_add_u32_e32 v223, 0x7000, v204
	s_waitcnt lgkmcnt(7)
	global_store_dwordx4 v204, v[44:47], s[8:9] sc1
	s_waitcnt lgkmcnt(6)
	global_store_dwordx4 v217, v[48:51], s[8:9] sc1
	s_waitcnt lgkmcnt(5)
	global_store_dwordx4 v218, v[52:55], s[8:9] sc1
	s_waitcnt lgkmcnt(4)
	global_store_dwordx4 v219, v[56:59], s[8:9] sc1
	s_waitcnt lgkmcnt(3)
	global_store_dwordx4 v220, v[60:63], s[8:9] sc1
	s_waitcnt lgkmcnt(2)
	global_store_dwordx4 v221, v[64:67], s[8:9] sc1
	s_waitcnt lgkmcnt(1)
	global_store_dwordx4 v222, v[68:71], s[8:9] sc1
	s_waitcnt lgkmcnt(0)
	global_store_dwordx4 v223, v[72:75], s[8:9] sc1
	s_branch .LBB0_1083
